# v4 + attention K/V staging via precomputed per-lane offsets (SGPR-base LDS-DMA) interleaved into the MFMA stream, 6-slot fragment ring
# baseline (speedup 1.0000x reference)
; #define LAS __attribute__((address_space(3)))
; __device__ __forceinline__ float uniform_f(float v) { return __int_as_float(__builtin_amdgcn_readfirstlane(__float_as_int(v))); }
; __device__ __forceinline__ void attn_stage(LAS unsigned char* lds, int buf, const bf16_t* kbase, const bf16_t* vbase, int k0, int wid, int lane) {
;     ...
;         for (int j = 0; j < 8; ++j) {
;             const int pi = wid * 8 + j, row = (pi - 32) * 8 + (lane >> 3), gch = (lane & 7) ^ ((row >> 1) & 7);
;             const bf16_t* src = vbase + (size_t)row * MTOK + k0 + gch * 8;
;             __builtin_amdgcn_global_load_lds((const unsigned*)src, (LAS unsigned*)(lds + buf * 65536 + pi * 1024), 16, 0, 0);
;         }
; __device__ __forceinline__ void attn_phase(LAS unsigned char* lds, const KArgs& P, int G, int c, int wv) {
;     ...
;         f32x16 O[8];
; #pragma unroll
;         for (int d = 0; d < 8; ++d)
; #pragma unroll
;             for (int i = 0; i < 16; ++i) O[d][i] = 0.f;
;         float lsum = 0.f;
;         const float sl2 = uniform_f(__builtin_amdgcn_exp2f(-(float)(h + 1)) * LOG2E);
;         const int nkt = 2 * qb + 2;
.LBB0_356:
	v_xor_b32_e32 v2, v2, v1
	v_ashrrev_i32_e32 v1, 31, v0
	v_lshlrev_b64 v[0:1], s74, v[0:1]
	v_lshl_add_u64 v[0:1], s[70:71], 0, v[0:1]
	s_lshl_b32 s70, s78, 1
	v_lshlrev_b32_e32 v2, 4, v2
	v_and_b32_e32 v178, s70, v2
	v_lshl_add_u64 v[0:1], v[0:1], 0, v[178:179]
	s_add_i32 m0, s10, s77
	s_add_i32 s12, s12, 2
	global_load_lds_dwordx4 v[0:1], off
	v_mov_b32_e32 v127, 0
	s_cmp_ge_u32 s69, s12
	v_mov_b32_e32 v126, v127
	v_mov_b32_e32 v125, v127
	v_mov_b32_e32 v124, v127
	v_mov_b32_e32 v123, v127
	v_mov_b32_e32 v122, v127
	v_mov_b32_e32 v121, v127
	v_mov_b32_e32 v120, v127
	v_mov_b32_e32 v119, v127
	v_mov_b32_e32 v118, v127
	v_mov_b32_e32 v117, v127
	v_mov_b32_e32 v116, v127
	v_mov_b32_e32 v115, v127
	v_mov_b32_e32 v114, v127
	v_mov_b32_e32 v113, v127
	v_mov_b32_e32 v112, v127
	v_mov_b32_e32 v111, v127
	v_mov_b32_e32 v110, v127
	v_mov_b32_e32 v109, v127
	v_mov_b32_e32 v108, v127
	v_mov_b32_e32 v107, v127
	v_mov_b32_e32 v106, v127
	v_mov_b32_e32 v105, v127
	v_mov_b32_e32 v104, v127
	v_mov_b32_e32 v103, v127
	v_mov_b32_e32 v102, v127
	v_mov_b32_e32 v101, v127
	v_mov_b32_e32 v100, v127
	v_mov_b32_e32 v99, v127
	v_mov_b32_e32 v98, v127
	v_mov_b32_e32 v97, v127
	v_mov_b32_e32 v96, v127
	v_mov_b32_e32 v95, v127
	v_mov_b32_e32 v94, v127
	v_mov_b32_e32 v93, v127
	v_mov_b32_e32 v92, v127
	v_mov_b32_e32 v91, v127
	v_mov_b32_e32 v90, v127
	v_mov_b32_e32 v89, v127
	v_mov_b32_e32 v88, v127
	v_mov_b32_e32 v87, v127
	v_mov_b32_e32 v86, v127
	v_mov_b32_e32 v85, v127
	v_mov_b32_e32 v84, v127
	v_mov_b32_e32 v83, v127
	v_mov_b32_e32 v82, v127
	v_mov_b32_e32 v81, v127
	v_mov_b32_e32 v80, v127
	v_mov_b32_e32 v79, v127
	v_mov_b32_e32 v78, v127
	v_mov_b32_e32 v77, v127
	v_mov_b32_e32 v76, v127
	v_mov_b32_e32 v75, v127
	v_mov_b32_e32 v74, v127
	v_mov_b32_e32 v73, v127
	v_mov_b32_e32 v72, v127
	v_mov_b32_e32 v71, v127
	v_mov_b32_e32 v70, v127
	v_mov_b32_e32 v69, v127
	v_mov_b32_e32 v68, v127
	v_mov_b32_e32 v67, v127
	v_mov_b32_e32 v66, v127
	v_mov_b32_e32 v65, v127
	v_mov_b32_e32 v64, v127
	v_mov_b32_e32 v63, v127
	v_mov_b32_e32 v62, v127
	v_mov_b32_e32 v61, v127
	v_mov_b32_e32 v60, v127
	v_mov_b32_e32 v59, v127
	v_mov_b32_e32 v58, v127
	v_mov_b32_e32 v57, v127
	v_mov_b32_e32 v56, v127
	v_mov_b32_e32 v55, v127
	v_mov_b32_e32 v54, v127
	v_mov_b32_e32 v53, v127
	v_mov_b32_e32 v52, v127
	v_mov_b32_e32 v51, v127
	v_mov_b32_e32 v50, v127
	v_mov_b32_e32 v49, v127
	v_mov_b32_e32 v48, v127
	v_mov_b32_e32 v47, v127
	v_mov_b32_e32 v46, v127
	v_mov_b32_e32 v45, v127
	v_mov_b32_e32 v44, v127
	v_mov_b32_e32 v43, v127
	v_mov_b32_e32 v42, v127
	v_mov_b32_e32 v41, v127
	v_mov_b32_e32 v40, v127
	v_mov_b32_e32 v39, v127
	v_mov_b32_e32 v38, v127
	v_mov_b32_e32 v37, v127
	v_mov_b32_e32 v36, v127
	v_mov_b32_e32 v35, v127
	v_mov_b32_e32 v34, v127
	v_mov_b32_e32 v33, v127
	v_mov_b32_e32 v32, v127
	v_mov_b32_e32 v31, v127
	v_mov_b32_e32 v30, v127
	v_mov_b32_e32 v29, v127
	v_mov_b32_e32 v28, v127
	v_mov_b32_e32 v27, v127
	v_mov_b32_e32 v26, v127
	v_mov_b32_e32 v25, v127
	v_mov_b32_e32 v24, v127
	v_mov_b32_e32 v23, v127
	v_mov_b32_e32 v22, v127
	v_mov_b32_e32 v21, v127
	v_mov_b32_e32 v20, v127
	v_mov_b32_e32 v19, v127
	v_mov_b32_e32 v18, v127
	v_mov_b32_e32 v17, v127
	v_mov_b32_e32 v16, v127
	v_mov_b32_e32 v15, v127
	v_mov_b32_e32 v14, v127
	v_mov_b32_e32 v13, v127
	v_mov_b32_e32 v12, v127
	v_mov_b32_e32 v11, v127
	v_mov_b32_e32 v10, v127
	v_mov_b32_e32 v9, v127
	v_mov_b32_e32 v8, v127
	v_mov_b32_e32 v7, v127
	v_mov_b32_e32 v6, v127
	v_mov_b32_e32 v5, v127
	v_mov_b32_e32 v4, v127
	v_mov_b32_e32 v3, v127
	v_mov_b32_e32 v2, v127
	v_mov_b32_e32 v1, v127
	v_mov_b32_e32 v0, v127
	v_mov_b32_e32 v212, v127
	s_cbranch_scc1 .LBB0_369
; __device__ __forceinline__ float uniform_f(float v) { return __int_as_float(__builtin_amdgcn_readfirstlane(__float_as_int(v))); }
; __device__ __forceinline__ void attn_phase(LAS unsigned char* lds, const KArgs& P, int G, int c, int wv) {
;     ...
;         const size_t tok0 = (size_t)b * SEQ;
;         const bf16_t* kbase = qk + tok0 * 4096 + 2048 + h * 256;
;         const bf16_t* vbase = vT + (size_t)(h * 256) * MTOK + tok0;
;         bf16x8 qf[8];
;         { const bf16_t* qp = qk + (tok0 + myq) * 4096 + h * 256 + sub * 128 + (lq >> 5) * 8;
; #pragma unroll
;           for (int ks = 0; ks < 8; ++ks) qf[ks] = *(const bf16x8*)(qp + ks * 16); }
;         f32x16 O[8];
; #pragma unroll
;         for (int d = 0; d < 8; ++d)
; #pragma unroll
;             for (int i = 0; i < 16; ++i) O[d][i] = 0.f;
;         float lsum = 0.f;
;         const float sl2 = uniform_f(__builtin_amdgcn_exp2f(-(float)(h + 1)) * LOG2E);
;         const int nkt = 2 * qb + 2;
;         int kt0 = 0; { const float dmax = 160.0f / sl2; const int kmin = q0 - 63 - (int)dmax; if (kmin > 0) kt0 = (kmin + 63) >> 6; if (kt0 > nkt - 1) kt0 = nkt - 1; }
;         { int lz0 = lane; asm volatile("" : "+v"(lz0)); attn_stage(lds, kt0 & 1, kbase, vbase, kt0 * 64, wid, lz0); }
;         for (int kt = kt0; kt < nkt; ++kt) {
	s_lshl_b64 s[70:71], s[62:63], 1
	s_add_u32 s70, s11, s70
	v_readlane_b32 s74, v255, 40
	s_mov_b32 s56, s90
	s_addc_u32 s71, s25, s71
	s_or_b32 s11, s81, 31
	s_lshl_b32 s25, s69, 16
	s_sub_i32 s6, s74, s6
	s_add_i32 s90, s76, 63
	s_lshl_b64 s[74:75], s[50:51], 13
	s_add_u32 s50, s72, s74
	s_addc_u32 s72, s73, s75
	s_lshl_b32 s73, s69, 7
	s_add_u32 s50, s50, s73
	s_addc_u32 s73, s72, 0
	v_readlane_b32 s72, v255, 41
	v_mov_b32_e32 v212, 0
	s_add_u32 s72, s72, s50
	v_readlane_b32 s50, v255, 42
	v_mul_f32_e32 v181, 0, v180
	v_add_f32_e32 v182, v180, v180
	v_mul_f32_e32 v183, 0x40400000, v180
	v_mul_f32_e32 v184, 4.0, v180
	v_mul_f32_e32 v185, 0x40a00000, v180
	v_mul_f32_e32 v186, 0x40c00000, v180
	v_mul_f32_e32 v187, 0x40e00000, v180
	v_mul_f32_e32 v188, 0x41800000, v180
	v_mul_f32_e32 v189, 0x41880000, v180
	v_mul_f32_e32 v190, 0x41900000, v180
	v_mul_f32_e32 v191, 0x41980000, v180
	v_mul_f32_e32 v192, 0x41a00000, v180
	v_mul_f32_e32 v193, 0x41a80000, v180
	v_mul_f32_e32 v194, 0x41b00000, v180
	v_mul_f32_e32 v195, 0x41b80000, v180
	v_mul_f32_e32 v196, 0x42000000, v180
	v_mul_f32_e32 v197, 0x42040000, v180
	v_mul_f32_e32 v198, 0x42080000, v180
	v_mul_f32_e32 v199, 0x420c0000, v180
	v_mul_f32_e32 v200, 0x42100000, v180
	v_mul_f32_e32 v201, 0x42140000, v180
	v_mul_f32_e32 v202, 0x42180000, v180
	v_mul_f32_e32 v203, 0x421c0000, v180
	v_mul_f32_e32 v204, 0x42400000, v180
	v_mul_f32_e32 v205, 0x42440000, v180
	v_mul_f32_e32 v206, 0x42480000, v180
	v_mul_f32_e32 v207, 0x424c0000, v180
	v_mul_f32_e32 v208, 0x42500000, v180
	v_mul_f32_e32 v209, 0x42540000, v180
	v_mul_f32_e32 v210, 0x42580000, v180
	v_mul_f32_e32 v211, 0x425c0000, v180
	s_addc_u32 s73, s50, s73
	v_mov_b32_e32 v0, 0
	v_mov_b32_e32 v1, v212
	v_mov_b32_e32 v2, v212
	v_mov_b32_e32 v3, v212
	v_mov_b32_e32 v4, v212
	v_mov_b32_e32 v5, v212
	v_mov_b32_e32 v6, v212
	v_mov_b32_e32 v7, v212
	v_mov_b32_e32 v8, v212
	v_mov_b32_e32 v9, v212
	v_mov_b32_e32 v10, v212
	v_mov_b32_e32 v11, v212
	v_mov_b32_e32 v12, v212
	v_mov_b32_e32 v13, v212
	v_mov_b32_e32 v14, v212
	v_mov_b32_e32 v15, v212
	v_mov_b32_e32 v16, 0
	v_mov_b32_e32 v17, v212
	v_mov_b32_e32 v18, v212
	v_mov_b32_e32 v19, v212
	v_mov_b32_e32 v20, v212
	v_mov_b32_e32 v21, v212
	v_mov_b32_e32 v22, v212
	v_mov_b32_e32 v23, v212
	v_mov_b32_e32 v24, v212
	v_mov_b32_e32 v25, v212
	v_mov_b32_e32 v26, v212
	v_mov_b32_e32 v27, v212
	v_mov_b32_e32 v28, v212
	v_mov_b32_e32 v29, v212
	v_mov_b32_e32 v30, v212
	v_mov_b32_e32 v31, v212
	v_mov_b32_e32 v32, 0
	v_mov_b32_e32 v33, v212
	v_mov_b32_e32 v34, v212
	v_mov_b32_e32 v35, v212
	v_mov_b32_e32 v36, v212
	v_mov_b32_e32 v37, v212
	v_mov_b32_e32 v38, v212
	v_mov_b32_e32 v39, v212
	v_mov_b32_e32 v40, v212
	v_mov_b32_e32 v41, v212
	v_mov_b32_e32 v42, v212
	v_mov_b32_e32 v43, v212
	v_mov_b32_e32 v44, v212
	v_mov_b32_e32 v45, v212
	v_mov_b32_e32 v46, v212
	v_mov_b32_e32 v47, v212
	v_mov_b32_e32 v48, 0
	v_mov_b32_e32 v49, v212
	v_mov_b32_e32 v50, v212
	v_mov_b32_e32 v51, v212
	v_mov_b32_e32 v52, v212
	v_mov_b32_e32 v53, v212
	v_mov_b32_e32 v54, v212
	v_mov_b32_e32 v55, v212
	v_mov_b32_e32 v56, v212
	v_mov_b32_e32 v57, v212
	v_mov_b32_e32 v58, v212
	v_mov_b32_e32 v59, v212
	v_mov_b32_e32 v60, v212
	v_mov_b32_e32 v61, v212
	v_mov_b32_e32 v62, v212
	v_mov_b32_e32 v63, v212
	v_mov_b32_e32 v64, 0
	v_mov_b32_e32 v65, v212
	v_mov_b32_e32 v66, v212
	v_mov_b32_e32 v67, v212
	v_mov_b32_e32 v68, v212
	v_mov_b32_e32 v69, v212
	v_mov_b32_e32 v70, v212
	v_mov_b32_e32 v71, v212
	v_mov_b32_e32 v72, v212
	v_mov_b32_e32 v73, v212
	v_mov_b32_e32 v74, v212
	v_mov_b32_e32 v75, v212
	v_mov_b32_e32 v76, v212
	v_mov_b32_e32 v77, v212
	v_mov_b32_e32 v78, v212
	v_mov_b32_e32 v79, v212
	v_mov_b32_e32 v80, 0
	v_mov_b32_e32 v81, v212
	v_mov_b32_e32 v82, v212
	v_mov_b32_e32 v83, v212
	v_mov_b32_e32 v84, v212
	v_mov_b32_e32 v85, v212
	v_mov_b32_e32 v86, v212
	v_mov_b32_e32 v87, v212
	v_mov_b32_e32 v88, v212
	v_mov_b32_e32 v89, v212
	v_mov_b32_e32 v90, v212
	v_mov_b32_e32 v91, v212
	v_mov_b32_e32 v92, v212
	v_mov_b32_e32 v93, v212
	v_mov_b32_e32 v94, v212
	v_mov_b32_e32 v95, v212
	v_mov_b32_e32 v96, 0
	v_mov_b32_e32 v97, v212
	v_mov_b32_e32 v98, v212
	v_mov_b32_e32 v99, v212
	v_mov_b32_e32 v100, v212
	v_mov_b32_e32 v101, v212
	v_mov_b32_e32 v102, v212
	v_mov_b32_e32 v103, v212
	v_mov_b32_e32 v104, v212
	v_mov_b32_e32 v105, v212
	v_mov_b32_e32 v106, v212
	v_mov_b32_e32 v107, v212
	v_mov_b32_e32 v108, v212
	v_mov_b32_e32 v109, v212
	v_mov_b32_e32 v110, v212
	v_mov_b32_e32 v111, v212
	v_mov_b32_e32 v112, 0
	v_mov_b32_e32 v113, v212
	v_mov_b32_e32 v114, v212
	v_mov_b32_e32 v115, v212
	v_mov_b32_e32 v116, v212
	v_mov_b32_e32 v117, v212
	v_mov_b32_e32 v118, v212
	v_mov_b32_e32 v119, v212
	v_mov_b32_e32 v120, v212
	v_mov_b32_e32 v121, v212
	v_mov_b32_e32 v122, v212
	v_mov_b32_e32 v123, v212
	v_mov_b32_e32 v124, v212
	v_mov_b32_e32 v125, v212
	v_mov_b32_e32 v126, v212
	v_mov_b32_e32 v127, v212
	s_waitcnt vmcnt(0)
	s_mov_b32 s32, 0
	s_branch .LBB0_359

; #define LAS __attribute__((address_space(3)))
; __device__ __forceinline__ void attn_stage(LAS unsigned char* lds, int buf, const bf16_t* kbase, const bf16_t* vbase, int k0, int wid, int lane) {
;     if (wid < 4) {
;         const int sub = wid >> 1;
; #pragma unroll
;         for (int j = 0; j < 8; ++j) {
;             const int pi = wid * 8 + j, row = (pi & 15) * 4 + (lane >> 4), gch = (lane & 15) ^ (row & 15);
;             const bf16_t* src = kbase + (size_t)(k0 + row) * 4096 + sub * 128 + gch * 8;
;             __builtin_amdgcn_global_load_lds((const unsigned*)src, (LAS unsigned*)(lds + buf * 65536 + pi * 1024), 16, 0, 0);
;         }
;     } else {
; #pragma unroll
;         for (int j = 0; j < 8; ++j) {
;             const int pi = wid * 8 + j, row = (pi - 32) * 8 + (lane >> 3), gch = (lane & 7) ^ ((row >> 1) & 7);
;             const bf16_t* src = vbase + (size_t)row * MTOK + k0 + gch * 8;
;             __builtin_amdgcn_global_load_lds((const unsigned*)src, (LAS unsigned*)(lds + buf * 65536 + pi * 1024), 16, 0, 0);
;         }
;     }
; __device__ __forceinline__ void attn_phase(LAS unsigned char* lds, const KArgs& P, int G, int c, int wv) {
;     ...
;         for (int kt = kt0; kt < nkt; ++kt) {
;             asm volatile("s_waitcnt vmcnt(0)" ::: "memory");
;             __syncthreads();
;             int lz = lane; asm volatile("" : "+v"(lz));
;             if (kt + 1 < nkt) attn_stage(lds, (kt + 1) & 1, kbase, vbase, (kt + 1) * 64, wid, lz);
.LBB0_359:
	s_add_i32 s69, s69, 1
	s_waitcnt vmcnt(0)
	s_cmp_ge_u32 s69, s12
	s_cselect_b64 s[74:75], -1, 0
	v_mov_b32_e32 v130, v246
	s_and_b64 vcc, exec, s[74:75]
	s_waitcnt lgkmcnt(0)
	s_barrier
	s_mov_b32 s99, 0
	s_cbranch_vccnz .LBB0_366
	s_and_b64 vcc, exec, s[18:19]
	s_and_b32 s78, s69, 1
	s_lshl_b32 s98, s78, 16
	s_cbranch_vccnz .Lattn_base_k
	s_mov_b64 s[100:101], s[72:73]
	s_branch .Lattn_base_done
.Lattn_base_k:
	s_add_i32 s100, s90, 1
	s_lshl_b32 s100, s100, 13
	s_add_u32 s100, s70, s100
	s_addc_u32 s101, s71, 0
.Lattn_base_done:
	s_cmp_lg_u32 s32, 0
	s_cbranch_scc1 .Lattn_fast_stage
	s_cbranch_vccnz .LBB0_363
	v_ashrrev_i32_e32 v131, 3, v130
	v_add_u32_e32 v132, 0xffffff00, v131
	v_add_u32_e32 v128, s83, v132
	v_lshrrev_b32_e32 v133, 1, v131
	v_ashrrev_i32_e32 v129, 31, v128
	s_lshl_b32 s50, s78, 16
	v_lshlrev_b64 v[128:129], 15, v[128:129]
	v_bitop3_b32 v133, v133, 7, v130 bitop3:0x48
	s_add_i32 s76, s50, 0
	v_lshl_or_b32 v128, v133, 4, v128
	v_lshl_add_u64 v[128:129], s[72:73], 0, v[128:129]
	s_add_i32 m0, s76, s84
	s_nop 0
	global_load_lds_dwordx4 v[128:129], off
	v_subrev_u32_e32 v192, s100, v128
	v_add_u32_e32 v128, s85, v132
	v_lshrrev_b32_e32 v133, 1, v128
	v_add_u32_e32 v128, s88, v131
	v_ashrrev_i32_e32 v129, 31, v128
	v_lshlrev_b64 v[128:129], 15, v[128:129]
	v_bitop3_b32 v133, v133, 7, v130 bitop3:0x48
	v_lshl_or_b32 v128, v133, 4, v128
	v_lshl_add_u64 v[128:129], s[72:73], 0, v[128:129]
	s_add_i32 m0, s76, s86
	s_nop 0
	global_load_lds_dwordx4 v[128:129], off
	v_subrev_u32_e32 v193, s100, v128
	v_add_u32_e32 v128, s87, v132
	v_lshrrev_b32_e32 v133, 1, v128
	v_add_u32_e32 v128, s43, v131
	v_ashrrev_i32_e32 v129, 31, v128
	v_lshlrev_b64 v[128:129], 15, v[128:129]
	v_bitop3_b32 v133, v133, 7, v130 bitop3:0x48
	v_lshl_or_b32 v128, v133, 4, v128
	v_lshl_add_u64 v[128:129], s[72:73], 0, v[128:129]
	s_add_i32 m0, s76, s93
	s_nop 0
	global_load_lds_dwordx4 v[128:129], off
	v_subrev_u32_e32 v194, s100, v128
	v_add_u32_e32 v128, s94, v132
	v_lshrrev_b32_e32 v133, 1, v128
	v_add_u32_e32 v128, s42, v131
	v_ashrrev_i32_e32 v129, 31, v128
	v_lshlrev_b64 v[128:129], 15, v[128:129]
	v_bitop3_b32 v133, v133, 7, v130 bitop3:0x48
	v_lshl_or_b32 v128, v133, 4, v128
	v_lshl_add_u64 v[128:129], s[72:73], 0, v[128:129]
	s_add_i32 m0, s76, s95
	s_nop 0
	global_load_lds_dwordx4 v[128:129], off
	v_subrev_u32_e32 v195, s100, v128
	v_add_u32_e32 v128, s96, v132
	v_lshrrev_b32_e32 v133, 1, v128
	v_add_u32_e32 v128, s41, v131
	v_ashrrev_i32_e32 v129, 31, v128
	v_lshlrev_b64 v[128:129], 15, v[128:129]
	v_bitop3_b32 v133, v133, 7, v130 bitop3:0x48
	v_lshl_or_b32 v128, v133, 4, v128
	v_lshl_add_u64 v[128:129], s[72:73], 0, v[128:129]
	s_add_i32 m0, s76, s97
	s_nop 0
	global_load_lds_dwordx4 v[128:129], off
	v_subrev_u32_e32 v196, s100, v128
	v_add_u32_e32 v128, s89, v132
	v_lshrrev_b32_e32 v133, 1, v128
	v_add_u32_e32 v128, s40, v131
	v_ashrrev_i32_e32 v129, 31, v128
	v_lshlrev_b64 v[128:129], 15, v[128:129]
	v_bitop3_b32 v133, v133, 7, v130 bitop3:0x48
	v_lshl_or_b32 v128, v133, 4, v128
	v_lshl_add_u64 v[128:129], s[72:73], 0, v[128:129]
	s_add_i32 m0, s76, s34
	s_nop 0
	global_load_lds_dwordx4 v[128:129], off
	v_subrev_u32_e32 v197, s100, v128
	v_add_u32_e32 v128, s35, v132
	v_lshrrev_b32_e32 v133, 1, v128
	v_add_u32_e32 v128, s7, v131
	v_ashrrev_i32_e32 v129, 31, v128
	v_lshlrev_b64 v[128:129], 15, v[128:129]
	v_bitop3_b32 v131, v133, 7, v130 bitop3:0x48
	v_lshl_or_b32 v128, v131, 4, v128
	v_lshl_add_u64 v[128:129], s[72:73], 0, v[128:129]
	s_add_i32 m0, s76, s44
	s_nop 0
	global_load_lds_dwordx4 v[128:129], off
	v_subrev_u32_e32 v198, s100, v128
	v_add_u32_e32 v128, s45, v132
	v_lshrrev_b32_e32 v129, 1, v128
	s_cbranch_execz .LBB0_364
	s_mov_b32 vcc_lo, 56
	s_mov_b64 s[76:77], 15
	s_mov_b64 s[78:79], s[72:73]
	s_branch .LBB0_365
.LBB0_363:
.LBB0_364:
	v_ashrrev_i32_e32 v131, 4, v130
	s_add_i32 s77, s48, s90
	v_add3_u32 v128, s77, v131, 1
	v_xor_b32_e32 v132, v131, v130
	v_ashrrev_i32_e32 v129, 31, v128
	s_lshl_b32 s50, s78, 16
	v_lshlrev_b64 v[128:129], 13, v[128:129]
	v_lshlrev_b32_e32 v132, 4, v132
	s_add_i32 s76, s50, 0
	v_lshl_add_u64 v[128:129], s[70:71], 0, v[128:129]
	v_and_b32_e32 v178, 0xf0, v132
	v_lshl_add_u64 v[128:129], v[128:129], 0, v[178:179]
	s_add_i32 m0, s76, s84
	s_add_i32 s77, s24, s90
	global_load_lds_dwordx4 v[128:129], off
	v_subrev_u32_e32 v192, s100, v128
	v_add_u32_e32 v128, s49, v131
	v_xor_b32_e32 v132, v128, v130
	v_add3_u32 v128, s77, v131, 1
	v_ashrrev_i32_e32 v129, 31, v128
	v_lshlrev_b64 v[128:129], 13, v[128:129]
	v_lshlrev_b32_e32 v132, 4, v132
	v_lshl_add_u64 v[128:129], s[70:71], 0, v[128:129]
	v_and_b32_e32 v132, 0xf0, v132
	v_mov_b32_e32 v133, v179
	v_lshl_add_u64 v[128:129], v[128:129], 0, v[132:133]
	s_add_i32 m0, s76, s86
	s_add_i32 s77, s5, s90
	global_load_lds_dwordx4 v[128:129], off
	v_subrev_u32_e32 v193, s100, v128
	v_add_u32_e32 v128, s92, v131
	v_xor_b32_e32 v132, v128, v130
	v_add3_u32 v128, s77, v131, 1
	v_ashrrev_i32_e32 v129, 31, v128
	v_lshlrev_b64 v[128:129], 13, v[128:129]
	v_lshlrev_b32_e32 v132, 4, v132
	v_lshl_add_u64 v[128:129], s[70:71], 0, v[128:129]
	v_and_b32_e32 v132, 0xf0, v132
	v_lshl_add_u64 v[128:129], v[128:129], 0, v[132:133]
	s_add_i32 m0, s76, s93
	s_add_i32 s77, s4, s90
	global_load_lds_dwordx4 v[128:129], off
	v_subrev_u32_e32 v194, s100, v128
	v_add_u32_e32 v128, s91, v131
	v_xor_b32_e32 v132, v128, v130
	v_add3_u32 v128, s77, v131, 1
	v_ashrrev_i32_e32 v129, 31, v128
	v_lshlrev_b64 v[128:129], 13, v[128:129]
	v_lshlrev_b32_e32 v132, 4, v132
	v_lshl_add_u64 v[128:129], s[70:71], 0, v[128:129]
	v_and_b32_e32 v132, 0xf0, v132
	v_lshl_add_u64 v[128:129], v[128:129], 0, v[132:133]
; __device__ __forceinline__ void attn_stage(LAS unsigned char* lds, int buf, const bf16_t* kbase, const bf16_t* vbase, int k0, int wid, int lane) {
;     if (wid < 4) {
;         const int sub = wid >> 1;
; #pragma unroll
;         for (int j = 0; j < 8; ++j) {
;             const int pi = wid * 8 + j, row = (pi & 15) * 4 + (lane >> 4), gch = (lane & 15) ^ (row & 15);
;             const bf16_t* src = kbase + (size_t)(k0 + row) * 4096 + sub * 128 + gch * 8;
;             __builtin_amdgcn_global_load_lds((const unsigned*)src, (LAS unsigned*)(lds + buf * 65536 + pi * 1024), 16, 0, 0);
;         }
;     } else {
; #pragma unroll
;         for (int j = 0; j < 8; ++j) {
;             const int pi = wid * 8 + j, row = (pi - 32) * 8 + (lane >> 3), gch = (lane & 7) ^ ((row >> 1) & 7);
;             const bf16_t* src = vbase + (size_t)row * MTOK + k0 + gch * 8;
;             __builtin_amdgcn_global_load_lds((const unsigned*)src, (LAS unsigned*)(lds + buf * 65536 + pi * 1024), 16, 0, 0);
;         }
;     }
; __device__ __forceinline__ void attn_phase(LAS unsigned char* lds, const KArgs& P, int G, int c, int wv) {
;     ...
;             if (kt + 1 < nkt) attn_stage(lds, (kt + 1) & 1, kbase, vbase, (kt + 1) * 64, wid, lz);
;             const int k0 = kt * 64;
;             if (k0 <= qw + 31) {
;                 const int rz = lz & 31, hz = lz >> 5, prz = (rz & 19) | ((rz & 4) << 1) | ((rz & 8) >> 1);
;                 const LAS unsigned char* kb = lds + (kt & 1) * 65536 + sub * 16384 + prz * 256;
;                 const int kx = (hz ^ (prz & 15)) * 16;
;                 const LAS unsigned char* vb = lds + (kt & 1) * 65536 + 32768 + rz * 128;
;                 const int vx = (hz ^ ((rz >> 1) & 7)) * 16;
;                 const int rel0 = k0 + 8 * hz - (qw + rz);
;                 const float tb = sl2 * (float)rel0 - Mb;
;                 const bool diag = (k0 + 63 > qw);
; #pragma unroll
;                 for (int half = 0; half < 2; ++half) {
;     ...
;                     f32x16 s;
; #pragma unroll
;                     for (int i = 0; i < 16; ++i) s[i] = 0.f;
;                     bf16x8 fr4[2];
;                     fr4[0] = KREAD(0);
;                     __builtin_amdgcn_sched_barrier(0);
; #pragma unroll
;                     for (int ks = 0; ks < 8; ++ks) {
;                         if (ks + 1 < 8) fr4[(ks + 1) & 1] = KREAD(ks + 1);
	s_add_i32 m0, s76, s95
	s_add_i32 s77, s30, s90
	global_load_lds_dwordx4 v[128:129], off
	v_subrev_u32_e32 v195, s100, v128
	v_add3_u32 v128, s77, v131, 1
	v_ashrrev_i32_e32 v129, 31, v128
	v_lshlrev_b64 v[128:129], 13, v[128:129]
	v_lshl_add_u64 v[128:129], s[70:71], 0, v[128:129]
	v_lshl_add_u64 v[128:129], v[128:129], 0, v[178:179]
	s_add_i32 m0, s76, s97
	s_add_i32 s77, s9, s90
	global_load_lds_dwordx4 v[128:129], off
	v_subrev_u32_e32 v196, s100, v128
	v_add_u32_e32 v128, s13, v131
	v_xor_b32_e32 v132, v128, v130
	v_add3_u32 v128, s77, v131, 1
	v_ashrrev_i32_e32 v129, 31, v128
	v_lshlrev_b64 v[128:129], 13, v[128:129]
	v_lshlrev_b32_e32 v132, 4, v132
	v_lshl_add_u64 v[128:129], s[70:71], 0, v[128:129]
	v_and_b32_e32 v178, 0xf0, v132
	v_lshl_add_u64 v[128:129], v[128:129], 0, v[178:179]
	s_add_i32 m0, s76, s34
	s_add_i32 s77, s8, s90
	global_load_lds_dwordx4 v[128:129], off
	v_subrev_u32_e32 v197, s100, v128
	v_add_u32_e32 v128, s14, v131
	v_xor_b32_e32 v132, v128, v130
	v_add3_u32 v128, s77, v131, 1
	v_ashrrev_i32_e32 v129, 31, v128
	v_lshlrev_b64 v[128:129], 13, v[128:129]
	v_lshlrev_b32_e32 v132, 4, v132
	v_lshl_add_u64 v[128:129], s[70:71], 0, v[128:129]
	v_and_b32_e32 v178, 0xf0, v132
	v_lshl_add_u64 v[128:129], v[128:129], 0, v[178:179]
	s_add_i32 m0, s76, s44
	s_add_i32 s76, s31, s90
	global_load_lds_dwordx4 v[128:129], off
	v_subrev_u32_e32 v198, s100, v128
	v_add_u32_e32 v129, s15, v131
	v_add3_u32 v128, s76, v131, 1
	s_movk_i32 vcc_lo, 0x78
	s_mov_b64 s[76:77], 13
	s_mov_b64 s[78:79], s[70:71]
.LBB0_365:
	v_xor_b32_e32 v131, v129, v130
	v_ashrrev_i32_e32 v129, 31, v128
	v_lshlrev_b64 v[128:129], s76, v[128:129]
	s_lshl_b32 s76, vcc_lo, 1
	v_lshlrev_b32_e32 v131, 4, v131
	v_lshl_add_u64 v[128:129], s[78:79], 0, v[128:129]
	v_and_b32_e32 v178, s76, v131
	v_lshl_add_u64 v[128:129], v[128:129], 0, v[178:179]
	s_add_i32 m0, s10, s50
	s_nop 0
	global_load_lds_dwordx4 v[128:129], off
	v_subrev_u32_e32 v199, s100, v128
	s_mov_b32 s32, 1
	s_branch .LBB0_366
.Lattn_fast_stage:
	s_sub_i32 s50, s90, 63
	s_cmp_gt_u32 s50, s11
	s_cbranch_scc1 .Lattn_fast_top
	s_mov_b32 s99, 1
	s_branch .LBB0_366
.Lattn_fast_top:
	s_add_i32 m0, s98, s84
	s_nop 0
	global_load_lds_dwordx4 v192, s[100:101]
	s_add_i32 m0, s98, s86
	s_nop 0
	global_load_lds_dwordx4 v193, s[100:101]
	s_add_i32 m0, s98, s93
	s_nop 0
	global_load_lds_dwordx4 v194, s[100:101]
	s_add_i32 m0, s98, s95
	s_nop 0
	global_load_lds_dwordx4 v195, s[100:101]
	s_add_i32 m0, s98, s97
	s_nop 0
	global_load_lds_dwordx4 v196, s[100:101]
	s_add_i32 m0, s98, s34
	s_nop 0
	global_load_lds_dwordx4 v197, s[100:101]
	s_add_i32 m0, s98, s44
	s_nop 0
	global_load_lds_dwordx4 v198, s[100:101]
	s_add_i32 m0, s10, s98
	s_nop 0
	global_load_lds_dwordx4 v199, s[100:101]
.LBB0_366:
	s_sub_i32 s50, s90, 63
	s_cmp_gt_u32 s50, s11
	s_cbranch_scc1 .LBB0_358
	v_and_b32_e32 v128, 31, v130
	v_ashrrev_i32_e32 v129, 5, v130
	v_and_b32_e32 v131, 19, v130
	v_lshlrev_b32_e32 v132, 1, v130
	v_lshrrev_b32_e32 v130, 1, v130
	s_and_b32 s50, s25, 0x10000
	v_and_b32_e32 v132, 8, v132
	v_and_b32_e32 v133, 4, v130
	s_add_i32 s50, s50, 0
	v_or3_b32 v131, v132, v131, v133
	s_add_i32 s76, s50, s46
	v_lshl_add_u32 v224, v131, 8, s76
	v_bitop3_b32 v131, v131, v129, 15 bitop3:0x6c
	v_bitop3_b32 v130, v130, v129, 7 bitop3:0x6c
	v_lshlrev_b32_e32 v129, 3, v129
	v_lshl_add_u32 v178, v128, 7, s50
	v_sub_u32_e32 v128, v129, v128
	s_add_i32 s50, s6, s90
	v_add_u32_e32 v128, s50, v128
	v_subrev_u32_e32 v214, 63, v128
	v_cvt_f32_i32_e32 v128, v214
	v_lshlrev_b32_e32 v225, 4, v131
	v_add_u32_e32 v226, v224, v225
	v_lshlrev_b32_e32 v213, 4, v130
	v_fma_f32 v215, v180, v128, -v248
	v_add_u32_e32 v235, v178, v213
	v_xad_u32 v233, v213, 32, v178
	v_xad_u32 v252, v213, 64, v178
	v_xad_u32 v234, v213, s80, v178
	v_xad_u32 v227, v225, 32, v224
	v_xad_u32 v228, v225, 64, v224
	v_xad_u32 v229, v225, s80, v224
	v_xad_u32 v230, v225, s39, v224
	s_movk_i32 s50, 0xa0
	v_xad_u32 v231, v225, s50, v224
	s_movk_i32 s50, 0xc0
	v_xad_u32 v232, v225, s50, v224
	s_movk_i32 s50, 0xe0
	v_xad_u32 v253, v225, s50, v224
	s_cmp_gt_u32 s90, s81
	s_cbranch_scc1 .Lattn_diag_path
	ds_read_b128 v[216:219], v226
	ds_read_b128 v[220:223], v227
	ds_read_b128 v[236:239], v228
	ds_read_b128 v[240:243], v229
	ds_read_b128 v[184:187], v230
	ds_read_b128 v[188:191], v231
	v_mov_b32_e32 v128, v215
	v_fmamk_f32 v129, v180, 0x3f800000, v215
	v_fmamk_f32 v130, v180, 0x40000000, v215
	v_fmamk_f32 v131, v180, 0x40400000, v215
	v_fmamk_f32 v132, v180, 0x40800000, v215
	v_fmamk_f32 v133, v180, 0x40a00000, v215
	v_fmamk_f32 v134, v180, 0x40c00000, v215
	v_fmamk_f32 v135, v180, 0x40e00000, v215
	v_fmamk_f32 v136, v180, 0x41800000, v215
	v_fmamk_f32 v137, v180, 0x41880000, v215
	v_fmamk_f32 v138, v180, 0x41900000, v215
	v_fmamk_f32 v139, v180, 0x41980000, v215
	v_fmamk_f32 v140, v180, 0x41a00000, v215
	v_fmamk_f32 v141, v180, 0x41a80000, v215
	v_fmamk_f32 v142, v180, 0x41b00000, v215
	v_fmamk_f32 v143, v180, 0x41b80000, v215
	s_nop 1
	s_waitcnt lgkmcnt(5)
	v_mfma_f32_32x32x16_bf16 v[128:143], v[216:219], v[144:147], v[128:143]
	ds_read_b128 v[216:219], v232
	s_waitcnt lgkmcnt(5)
	v_mfma_f32_32x32x16_bf16 v[128:143], v[220:223], v[148:151], v[128:143]
	ds_read_b128 v[220:223], v253
	s_waitcnt lgkmcnt(5)
	v_mfma_f32_32x32x16_bf16 v[128:143], v[236:239], v[152:155], v[128:143]
	ds_read_b128 v[236:239], v235 offset:32768
	s_waitcnt lgkmcnt(5)
	v_mfma_f32_32x32x16_bf16 v[128:143], v[240:243], v[156:159], v[128:143]
	ds_read_b128 v[240:243], v235 offset:36864
	s_waitcnt lgkmcnt(5)
	v_mfma_f32_32x32x16_bf16 v[128:143], v[184:187], v[160:163], v[128:143]
	ds_read_b128 v[184:187], v235 offset:40960
	s_waitcnt lgkmcnt(5)
; #define MFMA32(a, b, c) __builtin_amdgcn_mfma_f32_32x32x16_bf16((a), (b), (c), 0, 0, 0)
; __device__ __forceinline__ void attn_phase(LAS unsigned char* lds, const KArgs& P, int G, int c, int wv) {
;     ...
;                 for (int half = 0; half < 2; ++half) {
;     ...
;                     f32x16 s;
; #pragma unroll
;                     for (int i = 0; i < 16; ++i) s[i] = 0.f;
;                     bf16x8 fr4[2];
;                     fr4[0] = KREAD(0);
;                     __builtin_amdgcn_sched_barrier(0);
; #pragma unroll
;                     for (int ks = 0; ks < 8; ++ks) {
;                         if (ks + 1 < 8) fr4[(ks + 1) & 1] = KREAD(ks + 1);
;                         s = MFMA32(fr4[ks & 1], qf[ks], s);
;                         __builtin_amdgcn_sched_barrier(0);
;                     }
;                     bf16x8 pf0, pf1;
;                     { float pv[8];
; #pragma unroll
;                       for (int j = 0; j < 8; ++j) { const int cc = 32 * half + j;
;                           float p = __builtin_amdgcn_exp2f(s[j] + (tb + sl2 * (float)cc));
;                           if (diag && (rel0 + cc > 0)) p = 0.f;
;                           pv[j] = p; lsum += p; }
;                       u32x4 w; w.x = pk_bf16(pv[0], pv[1]); w.y = pk_bf16(pv[2], pv[3]); w.z = pk_bf16(pv[4], pv[5]); w.w = pk_bf16(pv[6], pv[7]);
;                       pf0 = __builtin_bit_cast(bf16x8, w); }
;                     __builtin_amdgcn_sched_barrier(0);
;                     u32x4 w1; float pe = 0.f;
; #pragma unroll
;                     for (int d = 0; d < 8; ++d) {
;                         O[d] = MFMA32(VREAD(2 * d), pf0, O[d]);
;                         { const int cc = 32 * half + 16 + d;
;                           float p = __builtin_amdgcn_exp2f(s[8 + d] + (tb + sl2 * (float)cc));
;                           if (diag && (rel0 + cc > 0)) p = 0.f;
;                           lsum += p;
;                           if (d & 1) w1[d >> 1] = pk_bf16(pe, p); else pe = p; }
;                         __builtin_amdgcn_sched_barrier(0);
;                     }
	v_mfma_f32_32x32x16_bf16 v[128:143], v[188:191], v[164:167], v[128:143]
	ds_read_b128 v[188:191], v235 offset:45056
	s_waitcnt lgkmcnt(5)
	v_mfma_f32_32x32x16_bf16 v[128:143], v[216:219], v[168:171], v[128:143]
	ds_read_b128 v[216:219], v235 offset:49152
	s_waitcnt lgkmcnt(5)
	v_mfma_f32_32x32x16_bf16 v[128:143], v[220:223], v[172:175], v[128:143]
	ds_read_b128 v[220:223], v235 offset:53248
	s_nop 11
	v_exp_f32_e32 v128, v128
	v_exp_f32_e32 v129, v129
	v_exp_f32_e32 v130, v130
	v_exp_f32_e32 v131, v131
	v_exp_f32_e32 v132, v132
	v_exp_f32_e32 v133, v133
	v_exp_f32_e32 v134, v134
	v_exp_f32_e32 v135, v135
	v_cvt_pk_bf16_f32 v200, v128, v129
	v_cvt_pk_bf16_f32 v201, v130, v131
	v_cvt_pk_bf16_f32 v202, v132, v133
	v_cvt_pk_bf16_f32 v203, v134, v135
	v_add_f32_e32 v183, v128, v129
	v_add_f32_e32 v208, v130, v131
	v_add_f32_e32 v209, v132, v133
	v_add_f32_e32 v210, v134, v135
	v_add_f32_e32 v183, v183, v208
	v_add_f32_e32 v209, v209, v210
	v_add_f32_e32 v183, v183, v209
	v_add_f32_e32 v212, v212, v183
	s_waitcnt lgkmcnt(5)
	v_mfma_f32_32x32x16_bf16 v[112:127], v[236:239], v[200:203], v[112:127]
	ds_read_b128 v[236:239], v235 offset:57344
	v_exp_f32_e32 v136, v136
	s_waitcnt lgkmcnt(5)
	v_mfma_f32_32x32x16_bf16 v[96:111], v[240:243], v[200:203], v[96:111]
	ds_read_b128 v[240:243], v235 offset:61440
	v_exp_f32_e32 v137, v137
	s_nop 0
	v_cvt_pk_bf16_f32 v204, v136, v137
	v_add_f32_e32 v183, v136, v137
	s_waitcnt lgkmcnt(5)
	v_mfma_f32_32x32x16_bf16 v[80:95], v[184:187], v[200:203], v[80:95]
	ds_read_b128 v[184:187], v233 offset:32768
	s_cmp_eq_u32 s99, 0
	s_cbranch_scc1 .Lattn_nodma_n0
	s_add_i32 m0, s98, s84
	s_nop 0
	global_load_lds_dwordx4 v192, s[100:101]
.Lattn_nodma_n0:
	v_exp_f32_e32 v138, v138
	s_waitcnt lgkmcnt(5)
	v_mfma_f32_32x32x16_bf16 v[64:79], v[188:191], v[200:203], v[64:79]
	ds_read_b128 v[188:191], v233 offset:36864
	v_exp_f32_e32 v139, v139
	s_nop 0
	v_cvt_pk_bf16_f32 v205, v138, v139
	v_add_f32_e32 v208, v138, v139
	s_waitcnt lgkmcnt(5)
	v_mfma_f32_32x32x16_bf16 v[48:63], v[216:219], v[200:203], v[48:63]
	ds_read_b128 v[216:219], v233 offset:40960
	v_exp_f32_e32 v140, v140
	s_waitcnt lgkmcnt(5)
	v_mfma_f32_32x32x16_bf16 v[32:47], v[220:223], v[200:203], v[32:47]
	ds_read_b128 v[220:223], v233 offset:45056
	v_exp_f32_e32 v141, v141
	s_nop 0
	v_cvt_pk_bf16_f32 v206, v140, v141
	v_add_f32_e32 v209, v140, v141
	s_waitcnt lgkmcnt(5)
	v_mfma_f32_32x32x16_bf16 v[16:31], v[236:239], v[200:203], v[16:31]
	ds_read_b128 v[236:239], v233 offset:49152
	s_cmp_eq_u32 s99, 0
	s_cbranch_scc1 .Lattn_nodma_n1
	s_add_i32 m0, s98, s86
	s_nop 0
	global_load_lds_dwordx4 v193, s[100:101]
.Lattn_nodma_n1:
	v_exp_f32_e32 v142, v142
	s_waitcnt lgkmcnt(5)
	v_mfma_f32_32x32x16_bf16 v[0:15], v[240:243], v[200:203], v[0:15]
	ds_read_b128 v[240:243], v233 offset:53248
	v_exp_f32_e32 v143, v143
	s_nop 0
	v_cvt_pk_bf16_f32 v207, v142, v143
	v_add_f32_e32 v210, v142, v143
	v_add_f32_e32 v183, v183, v208
	v_add_f32_e32 v209, v209, v210
	v_add_f32_e32 v183, v183, v209
	v_add_f32_e32 v212, v212, v183
	s_waitcnt lgkmcnt(5)
	v_mfma_f32_32x32x16_bf16 v[112:127], v[184:187], v[204:207], v[112:127]
	ds_read_b128 v[184:187], v233 offset:57344
	v_fmamk_f32 v128, v180, 0x42000000, v215
	v_fmamk_f32 v129, v180, 0x42040000, v215
	s_waitcnt lgkmcnt(5)
	v_mfma_f32_32x32x16_bf16 v[96:111], v[188:191], v[204:207], v[96:111]
	ds_read_b128 v[188:191], v233 offset:61440
	v_fmamk_f32 v130, v180, 0x42080000, v215
	v_fmamk_f32 v131, v180, 0x420c0000, v215
	s_waitcnt lgkmcnt(5)
	v_mfma_f32_32x32x16_bf16 v[80:95], v[216:219], v[204:207], v[80:95]
	ds_read_b128 v[216:219], v226 offset:8192
	s_cmp_eq_u32 s99, 0
	s_cbranch_scc1 .Lattn_nodma_n2
	s_add_i32 m0, s98, s93
	s_nop 0
	global_load_lds_dwordx4 v194, s[100:101]
.Lattn_nodma_n2:
	v_fmamk_f32 v132, v180, 0x42100000, v215
	v_fmamk_f32 v133, v180, 0x42140000, v215
	s_waitcnt lgkmcnt(5)
	v_mfma_f32_32x32x16_bf16 v[64:79], v[220:223], v[204:207], v[64:79]
	ds_read_b128 v[220:223], v227 offset:8192
	v_fmamk_f32 v134, v180, 0x42180000, v215
	v_fmamk_f32 v135, v180, 0x421c0000, v215
	s_waitcnt lgkmcnt(5)
	v_mfma_f32_32x32x16_bf16 v[48:63], v[236:239], v[204:207], v[48:63]
	ds_read_b128 v[236:239], v228 offset:8192
	v_fmamk_f32 v136, v180, 0x42400000, v215
	v_fmamk_f32 v137, v180, 0x42440000, v215
	s_waitcnt lgkmcnt(5)
	v_mfma_f32_32x32x16_bf16 v[32:47], v[240:243], v[204:207], v[32:47]
	ds_read_b128 v[240:243], v229 offset:8192
	v_fmamk_f32 v138, v180, 0x42480000, v215
	v_fmamk_f32 v139, v180, 0x424c0000, v215
	s_waitcnt lgkmcnt(5)
	v_mfma_f32_32x32x16_bf16 v[16:31], v[184:187], v[204:207], v[16:31]
	ds_read_b128 v[184:187], v230 offset:8192
	s_cmp_eq_u32 s99, 0
	s_cbranch_scc1 .Lattn_nodma_n3
	s_add_i32 m0, s98, s95
	s_nop 0
	global_load_lds_dwordx4 v195, s[100:101]
.Lattn_nodma_n3:
	v_fmamk_f32 v140, v180, 0x42500000, v215
	v_fmamk_f32 v141, v180, 0x42540000, v215
	s_waitcnt lgkmcnt(5)
	v_mfma_f32_32x32x16_bf16 v[0:15], v[188:191], v[204:207], v[0:15]
	ds_read_b128 v[188:191], v231 offset:8192
	v_fmamk_f32 v142, v180, 0x42580000, v215
	v_fmamk_f32 v143, v180, 0x425c0000, v215
	s_nop 1
	s_waitcnt lgkmcnt(5)
	v_mfma_f32_32x32x16_bf16 v[128:143], v[216:219], v[144:147], v[128:143]
	ds_read_b128 v[216:219], v232 offset:8192
	s_waitcnt lgkmcnt(5)
	v_mfma_f32_32x32x16_bf16 v[128:143], v[220:223], v[148:151], v[128:143]
	ds_read_b128 v[220:223], v253 offset:8192
	s_waitcnt lgkmcnt(5)
	v_mfma_f32_32x32x16_bf16 v[128:143], v[236:239], v[152:155], v[128:143]
	ds_read_b128 v[236:239], v252 offset:32768
	s_cmp_eq_u32 s99, 0
	s_cbranch_scc1 .Lattn_nodma_n4
	s_add_i32 m0, s98, s97
	s_nop 0
	global_load_lds_dwordx4 v196, s[100:101]
; #define MFMA32(a, b, c) __builtin_amdgcn_mfma_f32_32x32x16_bf16((a), (b), (c), 0, 0, 0)
; __device__ __forceinline__ void attn_phase(LAS unsigned char* lds, const KArgs& P, int G, int c, int wv) {
;     ...
;                     for (int ks = 0; ks < 8; ++ks) {
;                         if (ks + 1 < 8) fr4[(ks + 1) & 1] = KREAD(ks + 1);
;                         s = MFMA32(fr4[ks & 1], qf[ks], s);
;                         __builtin_amdgcn_sched_barrier(0);
;                     }
;                     bf16x8 pf0, pf1;
;                     { float pv[8];
; #pragma unroll
;                       for (int j = 0; j < 8; ++j) { const int cc = 32 * half + j;
;                           float p = __builtin_amdgcn_exp2f(s[j] + (tb + sl2 * (float)cc));
;                           if (diag && (rel0 + cc > 0)) p = 0.f;
;                           pv[j] = p; lsum += p; }
;                       u32x4 w; w.x = pk_bf16(pv[0], pv[1]); w.y = pk_bf16(pv[2], pv[3]); w.z = pk_bf16(pv[4], pv[5]); w.w = pk_bf16(pv[6], pv[7]);
;                       pf0 = __builtin_bit_cast(bf16x8, w); }
;                     __builtin_amdgcn_sched_barrier(0);
;                     u32x4 w1; float pe = 0.f;
; #pragma unroll
;                     for (int d = 0; d < 8; ++d) {
;                         O[d] = MFMA32(VREAD(2 * d), pf0, O[d]);
;                         { const int cc = 32 * half + 16 + d;
;                           float p = __builtin_amdgcn_exp2f(s[8 + d] + (tb + sl2 * (float)cc));
;                           if (diag && (rel0 + cc > 0)) p = 0.f;
;                           lsum += p;
;                           if (d & 1) w1[d >> 1] = pk_bf16(pe, p); else pe = p; }
;                         __builtin_amdgcn_sched_barrier(0);
;                     }
;                     pf1 = __builtin_bit_cast(bf16x8, w1);
; #pragma unroll
;                     for (int d = 0; d < 8; ++d) {
;                         O[d] = MFMA32(VREAD(2 * d + 1), pf1, O[d]);
;                         __builtin_amdgcn_sched_barrier(0);
;                     }
.Lattn_nodma_n4:
	s_waitcnt lgkmcnt(5)
	v_mfma_f32_32x32x16_bf16 v[128:143], v[240:243], v[156:159], v[128:143]
	ds_read_b128 v[240:243], v252 offset:36864
	s_waitcnt lgkmcnt(5)
	v_mfma_f32_32x32x16_bf16 v[128:143], v[184:187], v[160:163], v[128:143]
	ds_read_b128 v[184:187], v252 offset:40960
	s_waitcnt lgkmcnt(5)
	v_mfma_f32_32x32x16_bf16 v[128:143], v[188:191], v[164:167], v[128:143]
	ds_read_b128 v[188:191], v252 offset:45056
	s_waitcnt lgkmcnt(5)
	v_mfma_f32_32x32x16_bf16 v[128:143], v[216:219], v[168:171], v[128:143]
	ds_read_b128 v[216:219], v252 offset:49152
	s_cmp_eq_u32 s99, 0
	s_cbranch_scc1 .Lattn_nodma_n5
	s_add_i32 m0, s98, s34
	s_nop 0
	global_load_lds_dwordx4 v197, s[100:101]
.Lattn_nodma_n5:
	s_waitcnt lgkmcnt(5)
	v_mfma_f32_32x32x16_bf16 v[128:143], v[220:223], v[172:175], v[128:143]
	ds_read_b128 v[220:223], v252 offset:53248
	s_nop 11
	v_exp_f32_e32 v128, v128
	v_exp_f32_e32 v129, v129
	v_exp_f32_e32 v130, v130
	v_exp_f32_e32 v131, v131
	v_exp_f32_e32 v132, v132
	v_exp_f32_e32 v133, v133
	v_exp_f32_e32 v134, v134
	v_exp_f32_e32 v135, v135
	v_cvt_pk_bf16_f32 v200, v128, v129
	v_cvt_pk_bf16_f32 v201, v130, v131
	v_cvt_pk_bf16_f32 v202, v132, v133
	v_cvt_pk_bf16_f32 v203, v134, v135
	v_add_f32_e32 v183, v128, v129
	v_add_f32_e32 v208, v130, v131
	v_add_f32_e32 v209, v132, v133
	v_add_f32_e32 v210, v134, v135
	v_add_f32_e32 v183, v183, v208
	v_add_f32_e32 v209, v209, v210
	v_add_f32_e32 v183, v183, v209
	v_add_f32_e32 v212, v212, v183
	s_waitcnt lgkmcnt(5)
	v_mfma_f32_32x32x16_bf16 v[112:127], v[236:239], v[200:203], v[112:127]
	ds_read_b128 v[236:239], v252 offset:57344
	v_exp_f32_e32 v136, v136
	s_waitcnt lgkmcnt(5)
	v_mfma_f32_32x32x16_bf16 v[96:111], v[240:243], v[200:203], v[96:111]
	ds_read_b128 v[240:243], v252 offset:61440
	v_exp_f32_e32 v137, v137
	s_nop 0
	v_cvt_pk_bf16_f32 v204, v136, v137
	v_add_f32_e32 v183, v136, v137
	s_waitcnt lgkmcnt(5)
	v_mfma_f32_32x32x16_bf16 v[80:95], v[184:187], v[200:203], v[80:95]
	ds_read_b128 v[184:187], v234 offset:32768
	s_cmp_eq_u32 s99, 0
	s_cbranch_scc1 .Lattn_nodma_n6
	s_add_i32 m0, s98, s44
	s_nop 0
	global_load_lds_dwordx4 v198, s[100:101]
.Lattn_nodma_n6:
	v_exp_f32_e32 v138, v138
	s_waitcnt lgkmcnt(5)
	v_mfma_f32_32x32x16_bf16 v[64:79], v[188:191], v[200:203], v[64:79]
	ds_read_b128 v[188:191], v234 offset:36864
	v_exp_f32_e32 v139, v139
	s_nop 0
	v_cvt_pk_bf16_f32 v205, v138, v139
	v_add_f32_e32 v208, v138, v139
	s_waitcnt lgkmcnt(5)
	v_mfma_f32_32x32x16_bf16 v[48:63], v[216:219], v[200:203], v[48:63]
	ds_read_b128 v[216:219], v234 offset:40960
	v_exp_f32_e32 v140, v140
	s_waitcnt lgkmcnt(5)
	v_mfma_f32_32x32x16_bf16 v[32:47], v[220:223], v[200:203], v[32:47]
	ds_read_b128 v[220:223], v234 offset:45056
	v_exp_f32_e32 v141, v141
	s_nop 0
	v_cvt_pk_bf16_f32 v206, v140, v141
	v_add_f32_e32 v209, v140, v141
	s_waitcnt lgkmcnt(5)
	v_mfma_f32_32x32x16_bf16 v[16:31], v[236:239], v[200:203], v[16:31]
	ds_read_b128 v[236:239], v234 offset:49152
	s_cmp_eq_u32 s99, 0
	s_cbranch_scc1 .Lattn_nodma_n7
	s_add_i32 m0, s10, s98
	s_nop 0
	global_load_lds_dwordx4 v199, s[100:101]
.Lattn_nodma_n7:
	v_exp_f32_e32 v142, v142
	s_waitcnt lgkmcnt(5)
	v_mfma_f32_32x32x16_bf16 v[0:15], v[240:243], v[200:203], v[0:15]
	ds_read_b128 v[240:243], v234 offset:53248
	v_exp_f32_e32 v143, v143
	s_nop 0
	v_cvt_pk_bf16_f32 v207, v142, v143
	v_add_f32_e32 v210, v142, v143
	v_add_f32_e32 v183, v183, v208
	v_add_f32_e32 v209, v209, v210
	v_add_f32_e32 v183, v183, v209
	v_add_f32_e32 v212, v212, v183
	s_waitcnt lgkmcnt(5)
	v_mfma_f32_32x32x16_bf16 v[112:127], v[184:187], v[204:207], v[112:127]
	ds_read_b128 v[184:187], v234 offset:57344
	s_waitcnt lgkmcnt(5)
	v_mfma_f32_32x32x16_bf16 v[96:111], v[188:191], v[204:207], v[96:111]
	ds_read_b128 v[188:191], v234 offset:61440
	s_waitcnt lgkmcnt(5)
	v_mfma_f32_32x32x16_bf16 v[80:95], v[216:219], v[204:207], v[80:95]
	s_waitcnt lgkmcnt(4)
	v_mfma_f32_32x32x16_bf16 v[64:79], v[220:223], v[204:207], v[64:79]
	s_waitcnt lgkmcnt(3)
	v_mfma_f32_32x32x16_bf16 v[48:63], v[236:239], v[204:207], v[48:63]
	s_waitcnt lgkmcnt(2)
	v_mfma_f32_32x32x16_bf16 v[32:47], v[240:243], v[204:207], v[32:47]
	s_waitcnt lgkmcnt(1)
	v_mfma_f32_32x32x16_bf16 v[16:31], v[184:187], v[204:207], v[16:31]
	s_waitcnt lgkmcnt(0)
	v_mfma_f32_32x32x16_bf16 v[0:15], v[188:191], v[204:207], v[0:15]
	s_branch .LBB0_358
; #define MFMA32(a, b, c) __builtin_amdgcn_mfma_f32_32x32x16_bf16((a), (b), (c), 0, 0, 0)
; __device__ __forceinline__ void attn_stage(LAS unsigned char* lds, int buf, const bf16_t* kbase, const bf16_t* vbase, int k0, int wid, int lane) {
;     ...
;         for (int j = 0; j < 8; ++j) {
;             const int pi = wid * 8 + j, row = (pi & 15) * 4 + (lane >> 4), gch = (lane & 15) ^ (row & 15);
;             const bf16_t* src = kbase + (size_t)(k0 + row) * 4096 + sub * 128 + gch * 8;
; __device__ __forceinline__ void attn_phase(LAS unsigned char* lds, const KArgs& P, int G, int c, int wv) {
;     ...
; #pragma unroll
;                 for (int half = 0; half < 2; ++half) {
;     ...
;                     f32x16 s;
; #pragma unroll
;                     for (int i = 0; i < 16; ++i) s[i] = 0.f;
;                     bf16x8 fr4[2];
;                     fr4[0] = KREAD(0);
;                     __builtin_amdgcn_sched_barrier(0);
; #pragma unroll
;                     for (int ks = 0; ks < 8; ++ks) {
;                         if (ks + 1 < 8) fr4[(ks + 1) & 1] = KREAD(ks + 1);
;                         s = MFMA32(fr4[ks & 1], qf[ks], s);
;                         __builtin_amdgcn_sched_barrier(0);
;                     }
;                     bf16x8 pf0, pf1;
;                     { float pv[8];
; #pragma unroll
;                       for (int j = 0; j < 8; ++j) { const int cc = 32 * half + j;
;                           float p = __builtin_amdgcn_exp2f(s[j] + (tb + sl2 * (float)cc));
;                           if (diag && (rel0 + cc > 0)) p = 0.f;
;                           pv[j] = p; lsum += p; }
;                       u32x4 w; w.x = pk_bf16(pv[0], pv[1]); w.y = pk_bf16(pv[2], pv[3]); w.z = pk_bf16(pv[4], pv[5]); w.w = pk_bf16(pv[6], pv[7]);
;                       pf0 = __builtin_bit_cast(bf16x8, w); }
;                     __builtin_amdgcn_sched_barrier(0);
;                     u32x4 w1; float pe = 0.f;
; #pragma unroll
;                     for (int d = 0; d < 8; ++d) {
;                         O[d] = MFMA32(VREAD(2 * d), pf0, O[d]);
;                         { const int cc = 32 * half + 16 + d;
;                           float p = __builtin_amdgcn_exp2f(s[8 + d] + (tb + sl2 * (float)cc));
;                           if (diag && (rel0 + cc > 0)) p = 0.f;
;                           lsum += p;
;                           if (d & 1) w1[d >> 1] = pk_bf16(pe, p); else pe = p; }
.Lattn_diag_path:
	v_sub_u32_e32 v182, 0, v214
	v_mov_b32_e32 v181, 0xf149f2ca
	ds_read_b128 v[216:219], v226
	ds_read_b128 v[220:223], v227
	ds_read_b128 v[236:239], v228
	ds_read_b128 v[240:243], v229
	ds_read_b128 v[184:187], v230
	ds_read_b128 v[188:191], v231
	v_mov_b32_e32 v128, v215
	v_fmamk_f32 v129, v180, 0x3f800000, v215
	v_fmamk_f32 v130, v180, 0x40000000, v215
	v_fmamk_f32 v131, v180, 0x40400000, v215
	v_fmamk_f32 v132, v180, 0x40800000, v215
	v_fmamk_f32 v133, v180, 0x40a00000, v215
	v_fmamk_f32 v134, v180, 0x40c00000, v215
	v_fmamk_f32 v135, v180, 0x40e00000, v215
	v_fmamk_f32 v136, v180, 0x41800000, v215
	v_fmamk_f32 v137, v180, 0x41880000, v215
	v_fmamk_f32 v138, v180, 0x41900000, v215
	v_fmamk_f32 v139, v180, 0x41980000, v215
	v_fmamk_f32 v140, v180, 0x41a00000, v215
	v_fmamk_f32 v141, v180, 0x41a80000, v215
	v_fmamk_f32 v142, v180, 0x41b00000, v215
	v_fmamk_f32 v143, v180, 0x41b80000, v215
	v_cmp_gt_i32_e32 vcc, 0, v182
	s_nop 1
	v_cndmask_b32_e32 v128, v128, v181, vcc
	v_cmp_gt_i32_e32 vcc, 1, v182
	s_nop 1
	v_cndmask_b32_e32 v129, v129, v181, vcc
	v_cmp_gt_i32_e32 vcc, 2, v182
	s_nop 1
	v_cndmask_b32_e32 v130, v130, v181, vcc
	v_cmp_gt_i32_e32 vcc, 3, v182
	s_nop 1
	v_cndmask_b32_e32 v131, v131, v181, vcc
	v_cmp_gt_i32_e32 vcc, 4, v182
	s_nop 1
	v_cndmask_b32_e32 v132, v132, v181, vcc
	v_cmp_gt_i32_e32 vcc, 5, v182
	s_nop 1
	v_cndmask_b32_e32 v133, v133, v181, vcc
	v_cmp_gt_i32_e32 vcc, 6, v182
	s_nop 1
	v_cndmask_b32_e32 v134, v134, v181, vcc
	v_cmp_gt_i32_e32 vcc, 7, v182
	s_nop 1
	v_cndmask_b32_e32 v135, v135, v181, vcc
	v_cmp_gt_i32_e32 vcc, 16, v182
	s_nop 1
	v_cndmask_b32_e32 v136, v136, v181, vcc
	v_cmp_gt_i32_e32 vcc, 17, v182
	s_nop 1
	v_cndmask_b32_e32 v137, v137, v181, vcc
	v_cmp_gt_i32_e32 vcc, 18, v182
	s_nop 1
	v_cndmask_b32_e32 v138, v138, v181, vcc
	v_cmp_gt_i32_e32 vcc, 19, v182
	s_nop 1
	v_cndmask_b32_e32 v139, v139, v181, vcc
	v_cmp_gt_i32_e32 vcc, 20, v182
	s_nop 1
	v_cndmask_b32_e32 v140, v140, v181, vcc
	v_cmp_gt_i32_e32 vcc, 21, v182
	s_nop 1
	v_cndmask_b32_e32 v141, v141, v181, vcc
	v_cmp_gt_i32_e32 vcc, 22, v182
	s_nop 1
	v_cndmask_b32_e32 v142, v142, v181, vcc
	v_cmp_gt_i32_e32 vcc, 23, v182
	s_nop 1
	v_cndmask_b32_e32 v143, v143, v181, vcc
	s_nop 1
	s_waitcnt lgkmcnt(5)
	v_mfma_f32_32x32x16_bf16 v[128:143], v[216:219], v[144:147], v[128:143]
	ds_read_b128 v[216:219], v232
	s_waitcnt lgkmcnt(5)
	v_mfma_f32_32x32x16_bf16 v[128:143], v[220:223], v[148:151], v[128:143]
	ds_read_b128 v[220:223], v253
	s_waitcnt lgkmcnt(5)
	v_mfma_f32_32x32x16_bf16 v[128:143], v[236:239], v[152:155], v[128:143]
	ds_read_b128 v[236:239], v235 offset:32768
	s_waitcnt lgkmcnt(5)
	v_mfma_f32_32x32x16_bf16 v[128:143], v[240:243], v[156:159], v[128:143]
	ds_read_b128 v[240:243], v235 offset:36864
	s_waitcnt lgkmcnt(5)
	v_mfma_f32_32x32x16_bf16 v[128:143], v[184:187], v[160:163], v[128:143]
	ds_read_b128 v[184:187], v235 offset:40960
	s_waitcnt lgkmcnt(5)
	v_mfma_f32_32x32x16_bf16 v[128:143], v[188:191], v[164:167], v[128:143]
	ds_read_b128 v[188:191], v235 offset:45056
	s_waitcnt lgkmcnt(5)
	v_mfma_f32_32x32x16_bf16 v[128:143], v[216:219], v[168:171], v[128:143]
	ds_read_b128 v[216:219], v235 offset:49152
	s_waitcnt lgkmcnt(5)
	v_mfma_f32_32x32x16_bf16 v[128:143], v[220:223], v[172:175], v[128:143]
	ds_read_b128 v[220:223], v235 offset:53248
	s_nop 11
	v_exp_f32_e32 v128, v128
	v_exp_f32_e32 v129, v129
	v_exp_f32_e32 v130, v130
	v_exp_f32_e32 v131, v131
	v_exp_f32_e32 v132, v132
	v_exp_f32_e32 v133, v133
	v_exp_f32_e32 v134, v134
	v_exp_f32_e32 v135, v135
	v_cvt_pk_bf16_f32 v200, v128, v129
	v_cvt_pk_bf16_f32 v201, v130, v131
	v_cvt_pk_bf16_f32 v202, v132, v133
	v_cvt_pk_bf16_f32 v203, v134, v135
	v_add_f32_e32 v183, v128, v129
	v_add_f32_e32 v208, v130, v131
	v_add_f32_e32 v209, v132, v133
	v_add_f32_e32 v210, v134, v135
	v_add_f32_e32 v183, v183, v208
	v_add_f32_e32 v209, v209, v210
	v_add_f32_e32 v183, v183, v209
	v_add_f32_e32 v212, v212, v183
	s_waitcnt lgkmcnt(5)
	v_mfma_f32_32x32x16_bf16 v[112:127], v[236:239], v[200:203], v[112:127]
	ds_read_b128 v[236:239], v235 offset:57344
	v_exp_f32_e32 v136, v136
	s_waitcnt lgkmcnt(5)
	v_mfma_f32_32x32x16_bf16 v[96:111], v[240:243], v[200:203], v[96:111]
	ds_read_b128 v[240:243], v235 offset:61440
	v_exp_f32_e32 v137, v137
	s_nop 0
	v_cvt_pk_bf16_f32 v204, v136, v137
	v_add_f32_e32 v183, v136, v137
	s_waitcnt lgkmcnt(5)
	v_mfma_f32_32x32x16_bf16 v[80:95], v[184:187], v[200:203], v[80:95]
	ds_read_b128 v[184:187], v233 offset:32768
	s_cmp_eq_u32 s99, 0
	s_cbranch_scc1 .Lattn_nodma_d0
	s_add_i32 m0, s98, s84
	s_nop 0
	global_load_lds_dwordx4 v192, s[100:101]

; __device__ __forceinline__ void attn_stage(LAS unsigned char* lds, int buf, const bf16_t* kbase, const bf16_t* vbase, int k0, int wid, int lane) {
;     ...
;         for (int j = 0; j < 8; ++j) {
;             const int pi = wid * 8 + j, row = (pi & 15) * 4 + (lane >> 4), gch = (lane & 15) ^ (row & 15);
;             const bf16_t* src = kbase + (size_t)(k0 + row) * 4096 + sub * 128 + gch * 8;
;             __builtin_amdgcn_global_load_lds((const unsigned*)src, (LAS unsigned*)(lds + buf * 65536 + pi * 1024), 16, 0, 0);
;         }
;     } else {
; #pragma unroll
;         for (int j = 0; j < 8; ++j) {
;             const int pi = wid * 8 + j, row = (pi - 32) * 8 + (lane >> 3), gch = (lane & 7) ^ ((row >> 1) & 7);
;             const bf16_t* src = vbase + (size_t)row * MTOK + k0 + gch * 8;
; __device__ __forceinline__ void attn_phase(LAS unsigned char* lds, const KArgs& P, int G, int c, int wv) {
;     ...
;                       for (int j = 0; j < 8; ++j) { const int cc = 32 * half + j;
;                           float p = __builtin_amdgcn_exp2f(s[j] + (tb + sl2 * (float)cc));
;                           if (diag && (rel0 + cc > 0)) p = 0.f;
;                           pv[j] = p; lsum += p; }
;                       u32x4 w; w.x = pk_bf16(pv[0], pv[1]); w.y = pk_bf16(pv[2], pv[3]); w.z = pk_bf16(pv[4], pv[5]); w.w = pk_bf16(pv[6], pv[7]);
;                       pf0 = __builtin_bit_cast(bf16x8, w); }
;                     __builtin_amdgcn_sched_barrier(0);
;                     u32x4 w1; float pe = 0.f;
; #pragma unroll
;                     for (int d = 0; d < 8; ++d) {
;                         O[d] = MFMA32(VREAD(2 * d), pf0, O[d]);
;                         { const int cc = 32 * half + 16 + d;
;                           float p = __builtin_amdgcn_exp2f(s[8 + d] + (tb + sl2 * (float)cc));
;                           if (diag && (rel0 + cc > 0)) p = 0.f;
;                           lsum += p;
;                           if (d & 1) w1[d >> 1] = pk_bf16(pe, p); else pe = p; }
;                         __builtin_amdgcn_sched_barrier(0);
;                     }
;                     pf1 = __builtin_bit_cast(bf16x8, w1);
; #pragma unroll
;                     for (int d = 0; d < 8; ++d) {
;                         O[d] = MFMA32(VREAD(2 * d + 1), pf1, O[d]);
;                         __builtin_amdgcn_sched_barrier(0);
;                     }
.Lattn_nodma_d1:
	v_exp_f32_e32 v142, v142
	s_waitcnt lgkmcnt(5)
	v_mfma_f32_32x32x16_bf16 v[0:15], v[240:243], v[200:203], v[0:15]
	ds_read_b128 v[240:243], v233 offset:53248
	v_exp_f32_e32 v143, v143
	s_nop 0
	v_cvt_pk_bf16_f32 v207, v142, v143
	v_add_f32_e32 v210, v142, v143
	v_add_f32_e32 v183, v183, v208
	v_add_f32_e32 v209, v209, v210
	v_add_f32_e32 v183, v183, v209
	v_add_f32_e32 v212, v212, v183
	s_waitcnt lgkmcnt(5)
	v_mfma_f32_32x32x16_bf16 v[112:127], v[184:187], v[204:207], v[112:127]
	ds_read_b128 v[184:187], v233 offset:57344
	v_fmamk_f32 v128, v180, 0x42000000, v215
	v_fmamk_f32 v129, v180, 0x42040000, v215
	v_fmamk_f32 v130, v180, 0x42080000, v215
	v_fmamk_f32 v131, v180, 0x420c0000, v215
	v_fmamk_f32 v132, v180, 0x42100000, v215
	v_fmamk_f32 v133, v180, 0x42140000, v215
	v_fmamk_f32 v134, v180, 0x42180000, v215
	v_fmamk_f32 v135, v180, 0x421c0000, v215
	s_waitcnt lgkmcnt(5)
	v_mfma_f32_32x32x16_bf16 v[96:111], v[188:191], v[204:207], v[96:111]
	ds_read_b128 v[188:191], v233 offset:61440
	v_fmamk_f32 v136, v180, 0x42400000, v215
	v_fmamk_f32 v137, v180, 0x42440000, v215
	v_fmamk_f32 v138, v180, 0x42480000, v215
	v_fmamk_f32 v139, v180, 0x424c0000, v215
	v_fmamk_f32 v140, v180, 0x42500000, v215
	v_fmamk_f32 v141, v180, 0x42540000, v215
	v_fmamk_f32 v142, v180, 0x42580000, v215
	v_fmamk_f32 v143, v180, 0x425c0000, v215
	s_waitcnt lgkmcnt(5)
	v_mfma_f32_32x32x16_bf16 v[80:95], v[216:219], v[204:207], v[80:95]
	ds_read_b128 v[216:219], v226 offset:8192
	s_cmp_eq_u32 s99, 0
	s_cbranch_scc1 .Lattn_nodma_d2
	s_add_i32 m0, s98, s93
	s_nop 0
	global_load_lds_dwordx4 v194, s[100:101]
.Lattn_nodma_d2:
	v_cmp_gt_i32_e32 vcc, 32, v182
	s_nop 1
	v_cndmask_b32_e32 v128, v128, v181, vcc
	v_cmp_gt_i32_e32 vcc, 33, v182
	s_nop 1
	v_cndmask_b32_e32 v129, v129, v181, vcc
	v_cmp_gt_i32_e32 vcc, 34, v182
	s_nop 1
	s_waitcnt lgkmcnt(5)
	v_mfma_f32_32x32x16_bf16 v[64:79], v[220:223], v[204:207], v[64:79]
	ds_read_b128 v[220:223], v227 offset:8192
	v_cndmask_b32_e32 v130, v130, v181, vcc
	v_cmp_gt_i32_e32 vcc, 35, v182
	s_nop 1
	v_cndmask_b32_e32 v131, v131, v181, vcc
	v_cmp_gt_i32_e32 vcc, 36, v182
	s_nop 1
	v_cndmask_b32_e32 v132, v132, v181, vcc
	v_cmp_gt_i32_e32 vcc, 37, v182
	s_waitcnt lgkmcnt(5)
	v_mfma_f32_32x32x16_bf16 v[48:63], v[236:239], v[204:207], v[48:63]
	ds_read_b128 v[236:239], v228 offset:8192
	s_nop 1
	v_cndmask_b32_e32 v133, v133, v181, vcc
	v_cmp_gt_i32_e32 vcc, 38, v182
	s_nop 1
	v_cndmask_b32_e32 v134, v134, v181, vcc
	v_cmp_gt_i32_e32 vcc, 39, v182
	s_nop 1
	v_cndmask_b32_e32 v135, v135, v181, vcc
	s_waitcnt lgkmcnt(5)
	v_mfma_f32_32x32x16_bf16 v[32:47], v[240:243], v[204:207], v[32:47]
	ds_read_b128 v[240:243], v229 offset:8192
	v_cmp_gt_i32_e32 vcc, 48, v182
	s_nop 1
	v_cndmask_b32_e32 v136, v136, v181, vcc
	v_cmp_gt_i32_e32 vcc, 49, v182
	s_nop 1
	v_cndmask_b32_e32 v137, v137, v181, vcc
	v_cmp_gt_i32_e32 vcc, 50, v182
	s_nop 1
	s_waitcnt lgkmcnt(5)
	v_mfma_f32_32x32x16_bf16 v[16:31], v[184:187], v[204:207], v[16:31]
	ds_read_b128 v[184:187], v230 offset:8192
	s_cmp_eq_u32 s99, 0
	s_cbranch_scc1 .Lattn_nodma_d3
	s_add_i32 m0, s98, s95
	s_nop 0
	global_load_lds_dwordx4 v195, s[100:101]
.Lattn_nodma_d3:
	v_cndmask_b32_e32 v138, v138, v181, vcc
	v_cmp_gt_i32_e32 vcc, 51, v182
	s_nop 1
	v_cndmask_b32_e32 v139, v139, v181, vcc
	v_cmp_gt_i32_e32 vcc, 52, v182
	s_nop 1
	v_cndmask_b32_e32 v140, v140, v181, vcc
	v_cmp_gt_i32_e32 vcc, 53, v182
	s_waitcnt lgkmcnt(5)
	v_mfma_f32_32x32x16_bf16 v[0:15], v[188:191], v[204:207], v[0:15]
	ds_read_b128 v[188:191], v231 offset:8192
	s_nop 1
	v_cndmask_b32_e32 v141, v141, v181, vcc
	v_cmp_gt_i32_e32 vcc, 54, v182
	s_nop 1
	v_cndmask_b32_e32 v142, v142, v181, vcc
	v_cmp_gt_i32_e32 vcc, 55, v182
	s_nop 1
	v_cndmask_b32_e32 v143, v143, v181, vcc
	s_nop 1
	s_waitcnt lgkmcnt(5)
	v_mfma_f32_32x32x16_bf16 v[128:143], v[216:219], v[144:147], v[128:143]
	ds_read_b128 v[216:219], v232 offset:8192
	s_waitcnt lgkmcnt(5)
	v_mfma_f32_32x32x16_bf16 v[128:143], v[220:223], v[148:151], v[128:143]
	ds_read_b128 v[220:223], v253 offset:8192
	s_waitcnt lgkmcnt(5)
	v_mfma_f32_32x32x16_bf16 v[128:143], v[236:239], v[152:155], v[128:143]
	ds_read_b128 v[236:239], v252 offset:32768
	s_cmp_eq_u32 s99, 0
	s_cbranch_scc1 .Lattn_nodma_d4
	s_add_i32 m0, s98, s97
	s_nop 0
	global_load_lds_dwordx4 v196, s[100:101]
